# tile-coordinate computation: runtime division by the (always 4) group size replaced by shift and mask in all unit headers and rstd blocks
# speedup vs baseline: 1.0025x; 1.0025x over previous
; #define LAS __attribute__((address_space(3)))
;     __host__ __device__ bool next(int i, Unit& u) const {
;         const long L = (long)i * G + c; if (L >= nwg) return false;
;         int wgid = (int)L; { const int q = nwg / NXCD, r = nwg % NXCD, xcd = wgid % NXCD, off = wgid / NXCD; wgid = (xcd < r ? xcd * (q + 1) : r * (q + 1) + (xcd - r) * q) + off; }
;         const int nig = WGM * nN, gid = wgid / nig, fm = gid * WGM, gsz = (nM - fm) < WGM ? (nM - fm) : WGM;
;         u.pm = fm + ((wgid % nig) % gsz); u.pn = (wgid % nig) / gsz; u.idx = i; return true;
; template <class Sched>
; __device__ __forceinline__ void rstd_table(LAS float* rs, const float* ss, const Sched& S) {
;     Unit u;
;     for (int i = 0; i < 15 && S.next(i, u); ++i) if (threadIdx.x < BM) rs[i * BM + threadIdx.x] = rsqrtf(ss[u.pm * BM + threadIdx.x] * (1.0f / DM) + NORM_EPS);
; }
.LBB0_552:
	v_writelane_b32 v245, s96, 10
	s_xor_b64 s[0:1], s[4:5], -1
	v_writelane_b32 v245, s0, 11
	s_cmp_lt_i32 s88, 2
	s_nop 0
	v_writelane_b32 v245, s1, 12
	s_cselect_b64 s[0:1], -1, 0
	v_readlane_b32 s81, v245, 0
	s_lshl_b32 s6, s81, 3
	s_or_b32 s8, s6, s92
	s_and_b64 s[6:7], s[4:5], exec
	s_cselect_b32 s97, s8, s95
	s_add_u32 s68, s74, 0x7800000
	s_addc_u32 s69, s75, 0
	s_mul_i32 s6, s92, 0xe00000
	s_and_b64 s[4:5], s[4:5], exec
	s_cselect_b32 s5, s6, 0
	s_cselect_b32 s4, 0, 0
	s_add_u32 s64, s68, s5
	s_addc_u32 s65, s69, s4
	s_and_b64 s[0:1], s[0:1], s[2:3]
	s_andn2_b64 vcc, exec, s[0:1]
	s_mov_b64 s[4:5], -1
	s_cbranch_vccnz .LBB0_614
	s_ashr_i32 s0, s76, 31
	s_ashr_i32 s1, s97, 31
	s_cmpk_lt_i32 s97, 0xb00
	s_cselect_b64 s[6:7], -1, 0
	s_cmpk_gt_i32 s97, 0xaff
	s_cbranch_scc1 .LBB0_598
	s_movk_i32 s2, 0x100
	s_add_i32 s8, 0, 0x20000
	v_cmp_gt_u32_e64 s[2:3], s2, v153
	s_waitcnt vmcnt(4)
	v_lshl_add_u32 v0, v153, 2, s8
	s_and_saveexec_b64 s[8:9], s[2:3]
	s_cbranch_execz .LBB0_556
	s_lshr_b32 s10, s1, 29
	s_add_i32 s10, s97, s10
	s_and_b32 s11, s10, -8
	s_sub_i32 s11, s97, s11
	s_cmp_lt_i32 s11, 0
	s_movk_i32 s12, 0x161
	s_cselect_b32 s12, s12, 0x160
	s_mul_i32 s11, s11, s12
	s_ashr_i32 s10, s10, 3
	s_add_i32 s11, s11, s10
	s_mul_hi_i32 s10, s11, 0x2e8ba2e9
	s_lshr_b32 s12, s10, 31
	s_ashr_i32 s10, s10, 4
	s_add_i32 s10, s10, s12
	s_lshl_b32 s12, s10, 2
	s_mulk_i32 s10, 0x58
	s_sub_i32 s10, s11, s10
	s_ashr_i32 s11, s10, 31
	s_abs_i32 s10, s10
	v_mov_b32_e32 v3, 0
	s_and_b32 s10, s10, 3
	s_add_i32 s10, s12, s10
	v_lshl_or_b32 v2, s10, 8, v153
	v_lshl_add_u64 v[2:3], v[2:3], 2, s[24:25]
	global_load_dword v100, v[2:3], off
.LBB0_556:
	s_or_b64 exec, exec, s[8:9]
	s_add_u32 s8, s76, s97
	s_addc_u32 s9, s0, s1
	v_mov_b64_e32 v[2:3], 0xaff
	v_cmp_gt_i64_e32 vcc, s[8:9], v[2:3]
	s_cbranch_vccnz .LBB0_598
	s_and_saveexec_b64 s[10:11], s[2:3]
	s_cbranch_execz .LBB0_559
	s_ashr_i32 s12, s8, 31
	s_lshr_b32 s12, s12, 29
	s_add_i32 s12, s8, s12
	s_ashr_i32 s13, s12, 3
	s_and_b32 s12, s12, -8
	s_sub_i32 s12, s8, s12
	s_cmp_lt_i32 s12, 0
	s_movk_i32 s14, 0x161
	s_cselect_b32 s14, s14, 0x160
	s_mul_i32 s12, s12, s14
	s_add_i32 s12, s12, s13
	s_mul_hi_i32 s13, s12, 0x2e8ba2e9
	s_lshr_b32 s14, s13, 31
	s_ashr_i32 s13, s13, 4
	s_add_i32 s13, s13, s14
	s_lshl_b32 s14, s13, 2
	s_mulk_i32 s13, 0x58
	s_sub_i32 s12, s12, s13
	s_ashr_i32 s13, s12, 31
	s_abs_i32 s12, s12
	v_mov_b32_e32 v3, 0
	s_and_b32 s12, s12, 3
	s_add_i32 s12, s14, s12
	v_lshl_or_b32 v2, s12, 8, v153
	v_lshl_add_u64 v[2:3], v[2:3], 2, s[24:25]
	global_load_dword v101, v[2:3], off
.LBB0_559:
	s_or_b64 exec, exec, s[10:11]
	s_add_u32 s8, s8, s76
	s_addc_u32 s9, s9, s0
	v_mov_b64_e32 v[2:3], 0xaff
	v_cmp_gt_i64_e32 vcc, s[8:9], v[2:3]
	s_cbranch_vccnz .LBB0_598
	s_and_saveexec_b64 s[10:11], s[2:3]
	s_cbranch_execz .LBB0_562
	s_ashr_i32 s12, s8, 31
	s_lshr_b32 s12, s12, 29
	s_add_i32 s12, s8, s12
	s_ashr_i32 s13, s12, 3
	s_and_b32 s12, s12, -8
	s_sub_i32 s12, s8, s12
	s_cmp_lt_i32 s12, 0
	s_movk_i32 s14, 0x161
	s_cselect_b32 s14, s14, 0x160
	s_mul_i32 s12, s12, s14
	s_add_i32 s12, s12, s13
	s_mul_hi_i32 s13, s12, 0x2e8ba2e9
	s_lshr_b32 s14, s13, 31
	s_ashr_i32 s13, s13, 4
	s_add_i32 s13, s13, s14
	s_lshl_b32 s14, s13, 2
	s_mulk_i32 s13, 0x58
	s_sub_i32 s12, s12, s13
	s_ashr_i32 s13, s12, 31
	s_abs_i32 s12, s12
	v_mov_b32_e32 v3, 0
	s_and_b32 s12, s12, 3
	s_add_i32 s12, s14, s12
	v_lshl_or_b32 v2, s12, 8, v153
	v_lshl_add_u64 v[2:3], v[2:3], 2, s[24:25]
	global_load_dword v102, v[2:3], off
.LBB0_562:
	s_or_b64 exec, exec, s[10:11]
	s_add_u32 s8, s8, s76
	s_addc_u32 s9, s9, s0
	v_mov_b64_e32 v[2:3], 0xaff
	v_cmp_gt_i64_e32 vcc, s[8:9], v[2:3]
	s_cbranch_vccnz .LBB0_598
	s_and_saveexec_b64 s[10:11], s[2:3]
	s_cbranch_execz .LBB0_565
	s_ashr_i32 s12, s8, 31
	s_lshr_b32 s12, s12, 29
	s_add_i32 s12, s8, s12
	s_ashr_i32 s13, s12, 3
	s_and_b32 s12, s12, -8
	s_sub_i32 s12, s8, s12
	s_cmp_lt_i32 s12, 0
	s_movk_i32 s14, 0x161
	s_cselect_b32 s14, s14, 0x160
	s_mul_i32 s12, s12, s14
	s_add_i32 s12, s12, s13
	s_mul_hi_i32 s13, s12, 0x2e8ba2e9
	s_lshr_b32 s14, s13, 31
	s_ashr_i32 s13, s13, 4
	s_add_i32 s13, s13, s14
	s_lshl_b32 s14, s13, 2
	s_mulk_i32 s13, 0x58
	s_sub_i32 s12, s12, s13
	s_ashr_i32 s13, s12, 31
	s_abs_i32 s12, s12
	v_mov_b32_e32 v3, 0
	s_and_b32 s12, s12, 3
	s_add_i32 s12, s14, s12
	v_lshl_or_b32 v2, s12, 8, v153
	v_lshl_add_u64 v[2:3], v[2:3], 2, s[24:25]
	global_load_dword v103, v[2:3], off
.LBB0_565:
	s_or_b64 exec, exec, s[10:11]
	s_add_u32 s8, s8, s76
	s_addc_u32 s9, s9, s0
	v_mov_b64_e32 v[2:3], 0xaff
	v_cmp_gt_i64_e32 vcc, s[8:9], v[2:3]
	s_cbranch_vccnz .LBB0_598
	s_and_saveexec_b64 s[10:11], s[2:3]
	s_cbranch_execz .LBB0_568
	s_ashr_i32 s12, s8, 31
	s_lshr_b32 s12, s12, 29
	s_add_i32 s12, s8, s12
	s_ashr_i32 s13, s12, 3
	s_and_b32 s12, s12, -8
	s_sub_i32 s12, s8, s12
	s_cmp_lt_i32 s12, 0
	s_movk_i32 s14, 0x161
	s_cselect_b32 s14, s14, 0x160
	s_mul_i32 s12, s12, s14
	s_add_i32 s12, s12, s13
	s_mul_hi_i32 s13, s12, 0x2e8ba2e9
	s_lshr_b32 s14, s13, 31
	s_ashr_i32 s13, s13, 4
	s_add_i32 s13, s13, s14
	s_lshl_b32 s14, s13, 2
	s_mulk_i32 s13, 0x58
	s_sub_i32 s12, s12, s13
	s_ashr_i32 s13, s12, 31
	s_abs_i32 s12, s12
	v_mov_b32_e32 v3, 0
	s_and_b32 s12, s12, 3
	s_add_i32 s12, s14, s12
	v_lshl_or_b32 v2, s12, 8, v153
	v_lshl_add_u64 v[2:3], v[2:3], 2, s[24:25]
	global_load_dword v104, v[2:3], off
;     __host__ __device__ bool next(int i, Unit& u) const {
;         const long L = (long)i * G + c; if (L >= nwg) return false;
;         int wgid = (int)L; { const int q = nwg / NXCD, r = nwg % NXCD, xcd = wgid % NXCD, off = wgid / NXCD; wgid = (xcd < r ? xcd * (q + 1) : r * (q + 1) + (xcd - r) * q) + off; }
;         const int nig = WGM * nN, gid = wgid / nig, fm = gid * WGM, gsz = (nM - fm) < WGM ? (nM - fm) : WGM;
;         u.pm = fm + ((wgid % nig) % gsz); u.pn = (wgid % nig) / gsz; u.idx = i; return true;
; template <class Sched>
; __device__ __forceinline__ void rstd_table(LAS float* rs, const float* ss, const Sched& S) {
;     ...
;     for (int i = 0; i < 15 && S.next(i, u); ++i) if (threadIdx.x < BM) rs[i * BM + threadIdx.x] = rsqrtf(ss[u.pm * BM + threadIdx.x] * (1.0f / DM) + NORM_EPS);
.LBB0_568:
	s_or_b64 exec, exec, s[10:11]
	s_add_u32 s8, s8, s76
	s_addc_u32 s9, s9, s0
	v_mov_b64_e32 v[2:3], 0xaff
	v_cmp_gt_i64_e32 vcc, s[8:9], v[2:3]
	s_cbranch_vccnz .LBB0_598
	s_and_saveexec_b64 s[10:11], s[2:3]
	s_cbranch_execz .LBB0_571
	s_ashr_i32 s12, s8, 31
	s_lshr_b32 s12, s12, 29
	s_add_i32 s12, s8, s12
	s_ashr_i32 s13, s12, 3
	s_and_b32 s12, s12, -8
	s_sub_i32 s12, s8, s12
	s_cmp_lt_i32 s12, 0
	s_movk_i32 s14, 0x161
	s_cselect_b32 s14, s14, 0x160
	s_mul_i32 s12, s12, s14
	s_add_i32 s12, s12, s13
	s_mul_hi_i32 s13, s12, 0x2e8ba2e9
	s_lshr_b32 s14, s13, 31
	s_ashr_i32 s13, s13, 4
	s_add_i32 s13, s13, s14
	s_lshl_b32 s14, s13, 2
	s_mulk_i32 s13, 0x58
	s_sub_i32 s12, s12, s13
	s_ashr_i32 s13, s12, 31
	s_abs_i32 s12, s12
	v_mov_b32_e32 v3, 0
	s_and_b32 s12, s12, 3
	s_add_i32 s12, s14, s12
	v_lshl_or_b32 v2, s12, 8, v153
	v_lshl_add_u64 v[2:3], v[2:3], 2, s[24:25]
	global_load_dword v105, v[2:3], off
.LBB0_571:
	s_or_b64 exec, exec, s[10:11]
	s_add_u32 s8, s8, s76
	s_addc_u32 s9, s9, s0
	v_mov_b64_e32 v[2:3], 0xaff
	v_cmp_gt_i64_e32 vcc, s[8:9], v[2:3]
	s_cbranch_vccnz .LBB0_598
	s_and_saveexec_b64 s[10:11], s[2:3]
	s_cbranch_execz .LBB0_574
	s_ashr_i32 s12, s8, 31
	s_lshr_b32 s12, s12, 29
	s_add_i32 s12, s8, s12
	s_ashr_i32 s13, s12, 3
	s_and_b32 s12, s12, -8
	s_sub_i32 s12, s8, s12
	s_cmp_lt_i32 s12, 0
	s_movk_i32 s14, 0x161
	s_cselect_b32 s14, s14, 0x160
	s_mul_i32 s12, s12, s14
	s_add_i32 s12, s12, s13
	s_mul_hi_i32 s13, s12, 0x2e8ba2e9
	s_lshr_b32 s14, s13, 31
	s_ashr_i32 s13, s13, 4
	s_add_i32 s13, s13, s14
	s_lshl_b32 s14, s13, 2
	s_mulk_i32 s13, 0x58
	s_sub_i32 s12, s12, s13
	s_ashr_i32 s13, s12, 31
	s_abs_i32 s12, s12
	v_mov_b32_e32 v3, 0
	s_and_b32 s12, s12, 3
	s_add_i32 s12, s14, s12
	v_lshl_or_b32 v2, s12, 8, v153
	v_lshl_add_u64 v[2:3], v[2:3], 2, s[24:25]
	global_load_dword v106, v[2:3], off
.LBB0_574:
	s_or_b64 exec, exec, s[10:11]
	s_add_u32 s8, s8, s76
	s_addc_u32 s9, s9, s0
	v_mov_b64_e32 v[2:3], 0xaff
	v_cmp_gt_i64_e32 vcc, s[8:9], v[2:3]
	s_cbranch_vccnz .LBB0_598
	s_and_saveexec_b64 s[10:11], s[2:3]
	s_cbranch_execz .LBB0_577
	s_ashr_i32 s12, s8, 31
	s_lshr_b32 s12, s12, 29
	s_add_i32 s12, s8, s12
	s_ashr_i32 s13, s12, 3
	s_and_b32 s12, s12, -8
	s_sub_i32 s12, s8, s12
	s_cmp_lt_i32 s12, 0
	s_movk_i32 s14, 0x161
	s_cselect_b32 s14, s14, 0x160
	s_mul_i32 s12, s12, s14
	s_add_i32 s12, s12, s13
	s_mul_hi_i32 s13, s12, 0x2e8ba2e9
	s_lshr_b32 s14, s13, 31
	s_ashr_i32 s13, s13, 4
	s_add_i32 s13, s13, s14
	s_lshl_b32 s14, s13, 2
	s_mulk_i32 s13, 0x58
	s_sub_i32 s12, s12, s13
	s_ashr_i32 s13, s12, 31
	s_abs_i32 s12, s12
	v_mov_b32_e32 v3, 0
	s_and_b32 s12, s12, 3
	s_add_i32 s12, s14, s12
	v_lshl_or_b32 v2, s12, 8, v153
	v_lshl_add_u64 v[2:3], v[2:3], 2, s[24:25]
	global_load_dword v107, v[2:3], off
.LBB0_577:
	s_or_b64 exec, exec, s[10:11]
	s_add_u32 s8, s8, s76
	s_addc_u32 s9, s9, s0
	v_mov_b64_e32 v[2:3], 0xaff
	v_cmp_gt_i64_e32 vcc, s[8:9], v[2:3]
	s_cbranch_vccnz .LBB0_598
	s_and_saveexec_b64 s[10:11], s[2:3]
	s_cbranch_execz .LBB0_580
	s_ashr_i32 s12, s8, 31
	s_lshr_b32 s12, s12, 29
	s_add_i32 s12, s8, s12
	s_ashr_i32 s13, s12, 3
	s_and_b32 s12, s12, -8
	s_sub_i32 s12, s8, s12
	s_cmp_lt_i32 s12, 0
	s_movk_i32 s14, 0x161
	s_cselect_b32 s14, s14, 0x160
	s_mul_i32 s12, s12, s14
	s_add_i32 s12, s12, s13
	s_mul_hi_i32 s13, s12, 0x2e8ba2e9
	s_lshr_b32 s14, s13, 31
	s_ashr_i32 s13, s13, 4
	s_add_i32 s13, s13, s14
	s_lshl_b32 s14, s13, 2
	s_mulk_i32 s13, 0x58
	s_sub_i32 s12, s12, s13
	s_ashr_i32 s13, s12, 31
	s_abs_i32 s12, s12
	v_mov_b32_e32 v3, 0
	s_and_b32 s12, s12, 3
	s_add_i32 s12, s14, s12
	v_lshl_or_b32 v2, s12, 8, v153
	v_lshl_add_u64 v[2:3], v[2:3], 2, s[24:25]
	global_load_dword v108, v[2:3], off
.LBB0_580:
	s_or_b64 exec, exec, s[10:11]
	s_add_u32 s8, s8, s76
	s_addc_u32 s9, s9, s0
	v_mov_b64_e32 v[2:3], 0xaff
	v_cmp_gt_i64_e32 vcc, s[8:9], v[2:3]
	s_cbranch_vccnz .LBB0_598
	s_and_saveexec_b64 s[10:11], s[2:3]
	s_cbranch_execz .LBB0_583
	s_ashr_i32 s12, s8, 31
	s_lshr_b32 s12, s12, 29
	s_add_i32 s12, s8, s12
	s_ashr_i32 s13, s12, 3
	s_and_b32 s12, s12, -8
	s_sub_i32 s12, s8, s12
	s_cmp_lt_i32 s12, 0
	s_movk_i32 s14, 0x161
	s_cselect_b32 s14, s14, 0x160
	s_mul_i32 s12, s12, s14
	s_add_i32 s12, s12, s13
	s_mul_hi_i32 s13, s12, 0x2e8ba2e9
	s_lshr_b32 s14, s13, 31
	s_ashr_i32 s13, s13, 4
	s_add_i32 s13, s13, s14
	s_lshl_b32 s14, s13, 2
	s_mulk_i32 s13, 0x58
	s_sub_i32 s12, s12, s13
	s_ashr_i32 s13, s12, 31
	s_abs_i32 s12, s12
	v_mov_b32_e32 v3, 0
	s_and_b32 s12, s12, 3
	s_add_i32 s12, s14, s12
	v_lshl_or_b32 v2, s12, 8, v153
	v_lshl_add_u64 v[2:3], v[2:3], 2, s[24:25]
	global_load_dword v109, v[2:3], off
;     __host__ __device__ bool next(int i, Unit& u) const {
;         const long L = (long)i * G + c; if (L >= nwg) return false;
;         int wgid = (int)L; { const int q = nwg / NXCD, r = nwg % NXCD, xcd = wgid % NXCD, off = wgid / NXCD; wgid = (xcd < r ? xcd * (q + 1) : r * (q + 1) + (xcd - r) * q) + off; }
;         const int nig = WGM * nN, gid = wgid / nig, fm = gid * WGM, gsz = (nM - fm) < WGM ? (nM - fm) : WGM;
;         u.pm = fm + ((wgid % nig) % gsz); u.pn = (wgid % nig) / gsz; u.idx = i; return true;
; template <class Sched>
; __device__ __forceinline__ void rstd_table(LAS float* rs, const float* ss, const Sched& S) {
;     ...
;     for (int i = 0; i < 15 && S.next(i, u); ++i) if (threadIdx.x < BM) rs[i * BM + threadIdx.x] = rsqrtf(ss[u.pm * BM + threadIdx.x] * (1.0f / DM) + NORM_EPS);
.LBB0_583:
	s_or_b64 exec, exec, s[10:11]
	s_add_u32 s8, s8, s76
	s_addc_u32 s9, s9, s0
	v_mov_b64_e32 v[2:3], 0xaff
	v_cmp_gt_i64_e32 vcc, s[8:9], v[2:3]
	s_cbranch_vccnz .LBB0_598
	s_and_saveexec_b64 s[10:11], s[2:3]
	s_cbranch_execz .LBB0_586
	s_ashr_i32 s12, s8, 31
	s_lshr_b32 s12, s12, 29
	s_add_i32 s12, s8, s12
	s_ashr_i32 s13, s12, 3
	s_and_b32 s12, s12, -8
	s_sub_i32 s12, s8, s12
	s_cmp_lt_i32 s12, 0
	s_movk_i32 s14, 0x161
	s_cselect_b32 s14, s14, 0x160
	s_mul_i32 s12, s12, s14
	s_add_i32 s12, s12, s13
	s_mul_hi_i32 s13, s12, 0x2e8ba2e9
	s_lshr_b32 s14, s13, 31
	s_ashr_i32 s13, s13, 4
	s_add_i32 s13, s13, s14
	s_lshl_b32 s14, s13, 2
	s_mulk_i32 s13, 0x58
	s_sub_i32 s12, s12, s13
	s_ashr_i32 s13, s12, 31
	s_abs_i32 s12, s12
	v_mov_b32_e32 v3, 0
	s_and_b32 s12, s12, 3
	s_add_i32 s12, s14, s12
	v_lshl_or_b32 v2, s12, 8, v153
	v_lshl_add_u64 v[2:3], v[2:3], 2, s[24:25]
	global_load_dword v110, v[2:3], off
.LBB0_586:
	s_or_b64 exec, exec, s[10:11]
	s_add_u32 s8, s8, s76
	s_addc_u32 s9, s9, s0
	v_mov_b64_e32 v[2:3], 0xaff
	v_cmp_gt_i64_e32 vcc, s[8:9], v[2:3]
	s_cbranch_vccnz .LBB0_598
	s_and_saveexec_b64 s[10:11], s[2:3]
	s_cbranch_execz .LBB0_589
	s_ashr_i32 s12, s8, 31
	s_lshr_b32 s12, s12, 29
	s_add_i32 s12, s8, s12
	s_ashr_i32 s13, s12, 3
	s_and_b32 s12, s12, -8
	s_sub_i32 s12, s8, s12
	s_cmp_lt_i32 s12, 0
	s_movk_i32 s14, 0x161
	s_cselect_b32 s14, s14, 0x160
	s_mul_i32 s12, s12, s14
	s_add_i32 s12, s12, s13
	s_mul_hi_i32 s13, s12, 0x2e8ba2e9
	s_lshr_b32 s14, s13, 31
	s_ashr_i32 s13, s13, 4
	s_add_i32 s13, s13, s14
	s_lshl_b32 s14, s13, 2
	s_mulk_i32 s13, 0x58
	s_sub_i32 s12, s12, s13
	s_ashr_i32 s13, s12, 31
	s_abs_i32 s12, s12
	v_mov_b32_e32 v3, 0
	s_and_b32 s12, s12, 3
	s_add_i32 s12, s14, s12
	v_lshl_or_b32 v2, s12, 8, v153
	v_lshl_add_u64 v[2:3], v[2:3], 2, s[24:25]
	global_load_dword v111, v[2:3], off
.LBB0_589:
	s_or_b64 exec, exec, s[10:11]
	s_add_u32 s8, s8, s76
	s_addc_u32 s9, s9, s0
	v_mov_b64_e32 v[2:3], 0xaff
	v_cmp_gt_i64_e32 vcc, s[8:9], v[2:3]
	s_cbranch_vccnz .LBB0_598
	s_and_saveexec_b64 s[10:11], s[2:3]
	s_cbranch_execz .LBB0_592
	s_ashr_i32 s12, s8, 31
	s_lshr_b32 s12, s12, 29
	s_add_i32 s12, s8, s12
	s_ashr_i32 s13, s12, 3
	s_and_b32 s12, s12, -8
	s_sub_i32 s12, s8, s12
	s_cmp_lt_i32 s12, 0
	s_movk_i32 s14, 0x161
	s_cselect_b32 s14, s14, 0x160
	s_mul_i32 s12, s12, s14
	s_add_i32 s12, s12, s13
	s_mul_hi_i32 s13, s12, 0x2e8ba2e9
	s_lshr_b32 s14, s13, 31
	s_ashr_i32 s13, s13, 4
	s_add_i32 s13, s13, s14
	s_lshl_b32 s14, s13, 2
	s_mulk_i32 s13, 0x58
	s_sub_i32 s12, s12, s13
	s_ashr_i32 s13, s12, 31
	s_abs_i32 s12, s12
	v_mov_b32_e32 v3, 0
	s_and_b32 s12, s12, 3
	s_add_i32 s12, s14, s12
	v_lshl_or_b32 v2, s12, 8, v153
	v_lshl_add_u64 v[2:3], v[2:3], 2, s[24:25]
	global_load_dword v112, v[2:3], off
.LBB0_592:
	s_or_b64 exec, exec, s[10:11]
	s_add_u32 s8, s8, s76
	s_addc_u32 s9, s9, s0
	v_mov_b64_e32 v[2:3], 0xaff
	v_cmp_gt_i64_e32 vcc, s[8:9], v[2:3]
	s_cbranch_vccnz .LBB0_598
	s_and_saveexec_b64 s[10:11], s[2:3]
	s_cbranch_execz .LBB0_595
	s_ashr_i32 s12, s8, 31
	s_lshr_b32 s12, s12, 29
	s_add_i32 s12, s8, s12
	s_ashr_i32 s13, s12, 3
	s_and_b32 s12, s12, -8
	s_sub_i32 s12, s8, s12
	s_cmp_lt_i32 s12, 0
	s_movk_i32 s14, 0x161
	s_cselect_b32 s14, s14, 0x160
	s_mul_i32 s12, s12, s14
	s_add_i32 s12, s12, s13
	s_mul_hi_i32 s13, s12, 0x2e8ba2e9
	s_lshr_b32 s14, s13, 31
	s_ashr_i32 s13, s13, 4
	s_add_i32 s13, s13, s14
	s_lshl_b32 s14, s13, 2
	s_mulk_i32 s13, 0x58
	s_sub_i32 s12, s12, s13
	s_ashr_i32 s13, s12, 31
	s_abs_i32 s12, s12
	v_mov_b32_e32 v3, 0
	s_and_b32 s12, s12, 3
	s_add_i32 s12, s14, s12
	v_lshl_or_b32 v2, s12, 8, v153
	v_lshl_add_u64 v[2:3], v[2:3], 2, s[24:25]
	global_load_dword v113, v[2:3], off
.LBB0_595:
	s_or_b64 exec, exec, s[10:11]
	s_add_u32 s8, s8, s76
	s_addc_u32 s9, s9, s0
	v_mov_b64_e32 v[2:3], 0xb00
	v_cmp_lt_i64_e32 vcc, s[8:9], v[2:3]
	s_and_b64 s[10:11], vcc, s[2:3]
	s_and_saveexec_b64 s[2:3], s[10:11]
	s_cbranch_execz .LBB0_597
	s_ashr_i32 s9, s8, 31
	s_lshr_b32 s9, s9, 29
	s_add_i32 s9, s8, s9
	s_ashr_i32 s10, s9, 3
	s_and_b32 s9, s9, -8
	s_sub_i32 s8, s8, s9
	s_cmp_lt_i32 s8, 0
	s_movk_i32 s9, 0x161
	s_cselect_b32 s9, s9, 0x160
	s_mul_i32 s8, s8, s9
	s_add_i32 s8, s8, s10
	s_mul_hi_i32 s9, s8, 0x2e8ba2e9
	s_lshr_b32 s10, s9, 31
	s_ashr_i32 s9, s9, 4
	s_add_i32 s9, s9, s10
	s_lshl_b32 s10, s9, 2
	s_mulk_i32 s9, 0x58
	s_sub_i32 s8, s8, s9
	s_ashr_i32 s9, s8, 31
	s_abs_i32 s8, s8
	v_mov_b32_e32 v3, 0
	s_and_b32 s8, s8, 3
	s_add_i32 s8, s10, s8
	v_lshl_or_b32 v2, s8, 8, v153
	v_lshl_add_u64 v[2:3], v[2:3], 2, s[24:25]
	global_load_dword v114, v[2:3], off

;     __host__ __device__ bool next(int i, Unit& u) const {
;         const long L = (long)i * G + c; if (L >= nwg) return false;
;         int wgid = (int)L; { const int q = nwg / NXCD, r = nwg % NXCD, xcd = wgid % NXCD, off = wgid / NXCD; wgid = (xcd < r ? xcd * (q + 1) : r * (q + 1) + (xcd - r) * q) + off; }
;         const int nig = WGM * nN, gid = wgid / nig, fm = gid * WGM, gsz = (nM - fm) < WGM ? (nM - fm) : WGM;
;         u.pm = fm + ((wgid % nig) % gsz); u.pn = (wgid % nig) / gsz; u.idx = i; return true;
; template <class Epi, class Sched, bool ALIGN_EPI>
; __device__ __forceinline__ void gemm_phase(LAS unsigned char* lds, const Gemm g, const Sched& S, const Epi& E) {
;     ...
;         const bool has_next = S.next(ui + 1, nxt);
.LBB0_604:
	s_add_i32 s43, s43, 1
	s_mul_i32 s2, s43, s0
	s_mul_hi_u32 s3, s43, s76
	s_add_i32 s3, s3, s2
	s_mul_i32 s2, s43, s76
	s_add_u32 s16, s2, s97
	s_addc_u32 s17, s3, s1
	v_cmp_gt_i64_e32 vcc, s[16:17], v[142:143]
	v_cmp_lt_i64_e64 s[2:3], s[16:17], v[140:141]
	s_cbranch_vccnz .LBB0_606
	s_ashr_i32 s12, s16, 31
	s_lshr_b32 s12, s12, 29
	s_add_i32 s12, s16, s12
	s_ashr_i32 s13, s12, 3
	s_and_b32 s12, s12, -8
	s_sub_i32 s12, s16, s12
	s_cmp_lt_i32 s12, 0
	s_cselect_b32 s14, s34, 0x160
	s_mul_i32 s12, s12, s14
	s_add_i32 s12, s12, s13
	s_mul_hi_i32 s13, s12, 0x2e8ba2e9
	s_lshr_b32 s14, s13, 31
	s_ashr_i32 s13, s13, 4
	s_add_i32 s13, s13, s14
	s_lshl_b32 s14, s13, 2
	s_mulk_i32 s13, 0x58
	s_sub_i32 s13, s12, s13
	s_abs_i32 s12, s13
	s_mov_b32 s44, s43
	s_lshr_b32 s12, s13, 2
	s_and_b32 s13, s13, 3
	s_add_i32 s14, s14, s13

;     __host__ __device__ bool next(int i, Unit& u) const {
;         const long L = (long)i * G + c; if (L >= nwg) return false;
;         int wgid = (int)L; { const int q = nwg / NXCD, r = nwg % NXCD, xcd = wgid % NXCD, off = wgid / NXCD; wgid = (xcd < r ? xcd * (q + 1) : r * (q + 1) + (xcd - r) * q) + off; }
;         const int nig = WGM * nN, gid = wgid / nig, fm = gid * WGM, gsz = (nM - fm) < WGM ? (nM - fm) : WGM;
;         u.pm = fm + ((wgid % nig) % gsz); u.pn = (wgid % nig) / gsz; u.idx = i; return true;
.LBB0_710:
	s_ashr_i32 s4, s18, 3
	s_add_i32 s4, s24, s4
	s_ashr_i32 s5, s4, 31
	s_lshr_b32 s5, s5, 28
	s_add_i32 s5, s4, s5
	s_ashr_i32 s18, s5, 4
	s_lshl_b32 s18, s18, 2
	s_and_b32 s5, s5, -16
	s_sub_i32 s4, s4, s5
	s_abs_i32 s5, s4
	s_lshr_b32 s40, s4, 2
	s_and_b32 s4, s4, 3
	s_add_i32 s41, s18, s4

; #define LAS __attribute__((address_space(3)))
;     __host__ __device__ bool next(int i, Unit& u) const {
;         const long L = (long)i * G + c; if (L >= nwg) return false;
;         int wgid = (int)L; { const int q = nwg / NXCD, r = nwg % NXCD, xcd = wgid % NXCD, off = wgid / NXCD; wgid = (xcd < r ? xcd * (q + 1) : r * (q + 1) + (xcd - r) * q) + off; }
;         const int nig = WGM * nN, gid = wgid / nig, fm = gid * WGM, gsz = (nM - fm) < WGM ? (nM - fm) : WGM;
;         u.pm = fm + ((wgid % nig) % gsz); u.pn = (wgid % nig) / gsz; u.idx = i; return true;
; template <class Sched>
; __device__ __forceinline__ void rstd_table(LAS float* rs, const float* ss, const Sched& S) {
;     Unit u;
;     for (int i = 0; i < 15 && S.next(i, u); ++i) if (threadIdx.x < BM) rs[i * BM + threadIdx.x] = rsqrtf(ss[u.pm * BM + threadIdx.x] * (1.0f / DM) + NORM_EPS);
; }
.LBB0_817:
	s_cmp_lt_i32 s88, 4
	s_cselect_b64 s[0:1], -1, 0
	s_cmp_gt_i32 s89, 3
	s_cselect_b64 s[2:3], -1, 0
	s_and_b64 s[0:1], s[0:1], s[2:3]
	s_andn2_b64 vcc, exec, s[0:1]
	s_waitcnt lgkmcnt(0)
	s_cbranch_vccnz .LBB0_961
	s_ashr_i32 s0, s76, 31
	s_ashr_i32 s1, s97, 31
	s_cmpk_lt_i32 s97, 0x900
	s_cselect_b64 s[4:5], -1, 0
	s_cmpk_gt_i32 s97, 0x8ff
	s_cbranch_scc1 .LBB0_863
	s_movk_i32 s2, 0x100
	s_add_i32 s6, 0, 0x20000
	v_cmp_gt_u32_e64 s[2:3], s2, v153
	s_waitcnt vmcnt(0)
	v_lshl_add_u32 v0, v153, 2, s6
	s_and_saveexec_b64 s[6:7], s[2:3]
	s_cbranch_execz .LBB0_821
	s_lshr_b32 s10, s1, 29
	s_add_i32 s10, s97, s10
	s_and_b32 s11, s10, -8
	s_sub_i32 s11, s97, s11
	s_cmp_lt_i32 s11, 0
	s_movk_i32 s12, 0x121
	s_cselect_b32 s12, s12, 0x120
	s_mul_i32 s11, s11, s12
	s_ashr_i32 s10, s10, 3
	s_add_i32 s11, s11, s10
	s_mul_hi_i32 s10, s11, 0x38e38e39
	s_lshr_b32 s12, s10, 31
	s_ashr_i32 s10, s10, 4
	s_add_i32 s10, s10, s12
	s_lshl_b32 s12, s10, 2
	s_mulk_i32 s10, 0x48
	s_sub_i32 s10, s11, s10
	s_ashr_i32 s11, s10, 31
	s_abs_i32 s10, s10
	v_mov_b32_e32 v3, 0
	s_and_b32 s10, s10, 3
	s_add_i32 s10, s12, s10
	v_lshl_or_b32 v2, s10, 8, v153
	v_lshl_add_u64 v[2:3], v[2:3], 2, s[8:9]
	global_load_dword v100, v[2:3], off
.LBB0_821:
	s_or_b64 exec, exec, s[6:7]
	s_add_u32 s6, s76, s97
	s_addc_u32 s7, s0, s1
	v_mov_b64_e32 v[2:3], 0x8ff
	v_cmp_gt_i64_e32 vcc, s[6:7], v[2:3]
	s_cbranch_vccnz .LBB0_863
	s_and_saveexec_b64 s[10:11], s[2:3]
	s_cbranch_execz .LBB0_824
	s_ashr_i32 s12, s6, 31
	s_lshr_b32 s12, s12, 29
	s_add_i32 s12, s6, s12
	s_ashr_i32 s13, s12, 3
	s_and_b32 s12, s12, -8
	s_sub_i32 s12, s6, s12
	s_cmp_lt_i32 s12, 0
	s_movk_i32 s14, 0x121
	s_cselect_b32 s14, s14, 0x120
	s_mul_i32 s12, s12, s14
	s_add_i32 s12, s12, s13
	s_mul_hi_i32 s13, s12, 0x38e38e39
	s_lshr_b32 s14, s13, 31
	s_ashr_i32 s13, s13, 4
	s_add_i32 s13, s13, s14
	s_lshl_b32 s14, s13, 2
	s_mulk_i32 s13, 0x48
	s_sub_i32 s12, s12, s13
	s_ashr_i32 s13, s12, 31
	s_abs_i32 s12, s12
	v_mov_b32_e32 v3, 0
	s_and_b32 s12, s12, 3
	s_add_i32 s12, s14, s12
	v_lshl_or_b32 v2, s12, 8, v153
	v_lshl_add_u64 v[2:3], v[2:3], 2, s[8:9]
	global_load_dword v101, v[2:3], off
.LBB0_824:
	s_or_b64 exec, exec, s[10:11]
	s_add_u32 s6, s6, s76
	s_addc_u32 s7, s7, s0
	v_mov_b64_e32 v[2:3], 0x8ff
	v_cmp_gt_i64_e32 vcc, s[6:7], v[2:3]
	s_cbranch_vccnz .LBB0_863
	s_and_saveexec_b64 s[10:11], s[2:3]
	s_cbranch_execz .LBB0_827
	s_ashr_i32 s12, s6, 31
	s_lshr_b32 s12, s12, 29
	s_add_i32 s12, s6, s12
	s_ashr_i32 s13, s12, 3
	s_and_b32 s12, s12, -8
	s_sub_i32 s12, s6, s12
	s_cmp_lt_i32 s12, 0
	s_movk_i32 s14, 0x121
	s_cselect_b32 s14, s14, 0x120
	s_mul_i32 s12, s12, s14
	s_add_i32 s12, s12, s13
	s_mul_hi_i32 s13, s12, 0x38e38e39
	s_lshr_b32 s14, s13, 31
	s_ashr_i32 s13, s13, 4
	s_add_i32 s13, s13, s14
	s_lshl_b32 s14, s13, 2
	s_mulk_i32 s13, 0x48
	s_sub_i32 s12, s12, s13
	s_ashr_i32 s13, s12, 31
	s_abs_i32 s12, s12
	v_mov_b32_e32 v3, 0
	s_and_b32 s12, s12, 3
	s_add_i32 s12, s14, s12
	v_lshl_or_b32 v2, s12, 8, v153
	v_lshl_add_u64 v[2:3], v[2:3], 2, s[8:9]
	global_load_dword v102, v[2:3], off
.LBB0_827:
	s_or_b64 exec, exec, s[10:11]
	s_add_u32 s6, s6, s76
	s_addc_u32 s7, s7, s0
	v_mov_b64_e32 v[2:3], 0x8ff
	v_cmp_gt_i64_e32 vcc, s[6:7], v[2:3]
	s_cbranch_vccnz .LBB0_863
	s_and_saveexec_b64 s[10:11], s[2:3]
	s_cbranch_execz .LBB0_830
	s_ashr_i32 s12, s6, 31
	s_lshr_b32 s12, s12, 29
	s_add_i32 s12, s6, s12
	s_ashr_i32 s13, s12, 3
	s_and_b32 s12, s12, -8
	s_sub_i32 s12, s6, s12
	s_cmp_lt_i32 s12, 0
	s_movk_i32 s14, 0x121
	s_cselect_b32 s14, s14, 0x120
	s_mul_i32 s12, s12, s14
	s_add_i32 s12, s12, s13
	s_mul_hi_i32 s13, s12, 0x38e38e39
	s_lshr_b32 s14, s13, 31
	s_ashr_i32 s13, s13, 4
	s_add_i32 s13, s13, s14
	s_lshl_b32 s14, s13, 2
	s_mulk_i32 s13, 0x48
	s_sub_i32 s12, s12, s13
	s_ashr_i32 s13, s12, 31
	s_abs_i32 s12, s12
	v_mov_b32_e32 v3, 0
	s_and_b32 s12, s12, 3
	s_add_i32 s12, s14, s12
	v_lshl_or_b32 v2, s12, 8, v153
	v_lshl_add_u64 v[2:3], v[2:3], 2, s[8:9]
	global_load_dword v103, v[2:3], off
.LBB0_830:
	s_or_b64 exec, exec, s[10:11]
	s_add_u32 s6, s6, s76
	s_addc_u32 s7, s7, s0
	v_mov_b64_e32 v[2:3], 0x8ff
	v_cmp_gt_i64_e32 vcc, s[6:7], v[2:3]
	s_cbranch_vccnz .LBB0_863
	s_and_saveexec_b64 s[10:11], s[2:3]
	s_cbranch_execz .LBB0_833
	s_ashr_i32 s12, s6, 31
	s_lshr_b32 s12, s12, 29
	s_add_i32 s12, s6, s12
	s_ashr_i32 s13, s12, 3
	s_and_b32 s12, s12, -8
	s_sub_i32 s12, s6, s12
	s_cmp_lt_i32 s12, 0
	s_movk_i32 s14, 0x121
	s_cselect_b32 s14, s14, 0x120
	s_mul_i32 s12, s12, s14
	s_add_i32 s12, s12, s13
	s_mul_hi_i32 s13, s12, 0x38e38e39
	s_lshr_b32 s14, s13, 31
	s_ashr_i32 s13, s13, 4
	s_add_i32 s13, s13, s14
	s_lshl_b32 s14, s13, 2
	s_mulk_i32 s13, 0x48
	s_sub_i32 s12, s12, s13
	s_ashr_i32 s13, s12, 31
	s_abs_i32 s12, s12
	v_mov_b32_e32 v3, 0
	s_and_b32 s12, s12, 3
	s_add_i32 s12, s14, s12
	v_lshl_or_b32 v2, s12, 8, v153
	v_lshl_add_u64 v[2:3], v[2:3], 2, s[8:9]
	global_load_dword v104, v[2:3], off
.LBB0_833:
	s_or_b64 exec, exec, s[10:11]
	s_add_u32 s6, s6, s76
	s_addc_u32 s7, s7, s0
	v_mov_b64_e32 v[2:3], 0x8ff
	v_cmp_gt_i64_e32 vcc, s[6:7], v[2:3]
	s_cbranch_vccnz .LBB0_863
	s_and_saveexec_b64 s[10:11], s[2:3]
	s_cbranch_execz .LBB0_836
	s_ashr_i32 s12, s6, 31
	s_lshr_b32 s12, s12, 29
	s_add_i32 s12, s6, s12
	s_ashr_i32 s13, s12, 3
	s_and_b32 s12, s12, -8
	s_sub_i32 s12, s6, s12
	s_cmp_lt_i32 s12, 0
	s_movk_i32 s14, 0x121
	s_cselect_b32 s14, s14, 0x120
	s_mul_i32 s12, s12, s14
	s_add_i32 s12, s12, s13
	s_mul_hi_i32 s13, s12, 0x38e38e39
	s_lshr_b32 s14, s13, 31
	s_ashr_i32 s13, s13, 4
	s_add_i32 s13, s13, s14
	s_lshl_b32 s14, s13, 2
	s_mulk_i32 s13, 0x48
	s_sub_i32 s12, s12, s13
	s_ashr_i32 s13, s12, 31
	s_abs_i32 s12, s12
	v_mov_b32_e32 v3, 0
	s_and_b32 s12, s12, 3
	s_add_i32 s12, s14, s12
	v_lshl_or_b32 v2, s12, 8, v153
	v_lshl_add_u64 v[2:3], v[2:3], 2, s[8:9]
	global_load_dword v105, v[2:3], off
;     __host__ __device__ bool next(int i, Unit& u) const {
;         const long L = (long)i * G + c; if (L >= nwg) return false;
;         int wgid = (int)L; { const int q = nwg / NXCD, r = nwg % NXCD, xcd = wgid % NXCD, off = wgid / NXCD; wgid = (xcd < r ? xcd * (q + 1) : r * (q + 1) + (xcd - r) * q) + off; }
;         const int nig = WGM * nN, gid = wgid / nig, fm = gid * WGM, gsz = (nM - fm) < WGM ? (nM - fm) : WGM;
;         u.pm = fm + ((wgid % nig) % gsz); u.pn = (wgid % nig) / gsz; u.idx = i; return true;
; template <class Sched>
; __device__ __forceinline__ void rstd_table(LAS float* rs, const float* ss, const Sched& S) {
;     ...
;     for (int i = 0; i < 15 && S.next(i, u); ++i) if (threadIdx.x < BM) rs[i * BM + threadIdx.x] = rsqrtf(ss[u.pm * BM + threadIdx.x] * (1.0f / DM) + NORM_EPS);
.LBB0_836:
	s_or_b64 exec, exec, s[10:11]
	s_add_u32 s6, s6, s76
	s_addc_u32 s7, s7, s0
	v_mov_b64_e32 v[2:3], 0x8ff
	v_cmp_gt_i64_e32 vcc, s[6:7], v[2:3]
	s_cbranch_vccnz .LBB0_863
	s_and_saveexec_b64 s[10:11], s[2:3]
	s_cbranch_execz .LBB0_839
	s_ashr_i32 s12, s6, 31
	s_lshr_b32 s12, s12, 29
	s_add_i32 s12, s6, s12
	s_ashr_i32 s13, s12, 3
	s_and_b32 s12, s12, -8
	s_sub_i32 s12, s6, s12
	s_cmp_lt_i32 s12, 0
	s_movk_i32 s14, 0x121
	s_cselect_b32 s14, s14, 0x120
	s_mul_i32 s12, s12, s14
	s_add_i32 s12, s12, s13
	s_mul_hi_i32 s13, s12, 0x38e38e39
	s_lshr_b32 s14, s13, 31
	s_ashr_i32 s13, s13, 4
	s_add_i32 s13, s13, s14
	s_lshl_b32 s14, s13, 2
	s_mulk_i32 s13, 0x48
	s_sub_i32 s12, s12, s13
	s_ashr_i32 s13, s12, 31
	s_abs_i32 s12, s12
	v_mov_b32_e32 v3, 0
	s_and_b32 s12, s12, 3
	s_add_i32 s12, s14, s12
	v_lshl_or_b32 v2, s12, 8, v153
	v_lshl_add_u64 v[2:3], v[2:3], 2, s[8:9]
	global_load_dword v106, v[2:3], off
.LBB0_839:
	s_or_b64 exec, exec, s[10:11]
	s_add_u32 s6, s6, s76
	s_addc_u32 s7, s7, s0
	v_mov_b64_e32 v[2:3], 0x8ff
	v_cmp_gt_i64_e32 vcc, s[6:7], v[2:3]
	s_cbranch_vccnz .LBB0_863
	s_and_saveexec_b64 s[10:11], s[2:3]
	s_cbranch_execz .LBB0_842
	s_ashr_i32 s12, s6, 31
	s_lshr_b32 s12, s12, 29
	s_add_i32 s12, s6, s12
	s_ashr_i32 s13, s12, 3
	s_and_b32 s12, s12, -8
	s_sub_i32 s12, s6, s12
	s_cmp_lt_i32 s12, 0
	s_movk_i32 s14, 0x121
	s_cselect_b32 s14, s14, 0x120
	s_mul_i32 s12, s12, s14
	s_add_i32 s12, s12, s13
	s_mul_hi_i32 s13, s12, 0x38e38e39
	s_lshr_b32 s14, s13, 31
	s_ashr_i32 s13, s13, 4
	s_add_i32 s13, s13, s14
	s_lshl_b32 s14, s13, 2
	s_mulk_i32 s13, 0x48
	s_sub_i32 s12, s12, s13
	s_ashr_i32 s13, s12, 31
	s_abs_i32 s12, s12
	v_mov_b32_e32 v3, 0
	s_and_b32 s12, s12, 3
	s_add_i32 s12, s14, s12
	v_lshl_or_b32 v2, s12, 8, v153
	v_lshl_add_u64 v[2:3], v[2:3], 2, s[8:9]
	global_load_dword v107, v[2:3], off
.LBB0_842:
	s_or_b64 exec, exec, s[10:11]
	s_add_u32 s6, s6, s76
	s_addc_u32 s7, s7, s0
	v_mov_b64_e32 v[2:3], 0x8ff
	v_cmp_gt_i64_e32 vcc, s[6:7], v[2:3]
	s_cbranch_vccnz .LBB0_863
	s_and_saveexec_b64 s[10:11], s[2:3]
	s_cbranch_execz .LBB0_845
	s_ashr_i32 s12, s6, 31
	s_lshr_b32 s12, s12, 29
	s_add_i32 s12, s6, s12
	s_ashr_i32 s13, s12, 3
	s_and_b32 s12, s12, -8
	s_sub_i32 s12, s6, s12
	s_cmp_lt_i32 s12, 0
	s_movk_i32 s14, 0x121
	s_cselect_b32 s14, s14, 0x120
	s_mul_i32 s12, s12, s14
	s_add_i32 s12, s12, s13
	s_mul_hi_i32 s13, s12, 0x38e38e39
	s_lshr_b32 s14, s13, 31
	s_ashr_i32 s13, s13, 4
	s_add_i32 s13, s13, s14
	s_lshl_b32 s14, s13, 2
	s_mulk_i32 s13, 0x48
	s_sub_i32 s12, s12, s13
	s_ashr_i32 s13, s12, 31
	s_abs_i32 s12, s12
	v_mov_b32_e32 v3, 0
	s_and_b32 s12, s12, 3
	s_add_i32 s12, s14, s12
	v_lshl_or_b32 v2, s12, 8, v153
	v_lshl_add_u64 v[2:3], v[2:3], 2, s[8:9]
	global_load_dword v108, v[2:3], off
.LBB0_845:
	s_or_b64 exec, exec, s[10:11]
	s_add_u32 s6, s6, s76
	s_addc_u32 s7, s7, s0
	v_mov_b64_e32 v[2:3], 0x8ff
	v_cmp_gt_i64_e32 vcc, s[6:7], v[2:3]
	s_cbranch_vccnz .LBB0_863
	s_and_saveexec_b64 s[10:11], s[2:3]
	s_cbranch_execz .LBB0_848
	s_ashr_i32 s12, s6, 31
	s_lshr_b32 s12, s12, 29
	s_add_i32 s12, s6, s12
	s_ashr_i32 s13, s12, 3
	s_and_b32 s12, s12, -8
	s_sub_i32 s12, s6, s12
	s_cmp_lt_i32 s12, 0
	s_movk_i32 s14, 0x121
	s_cselect_b32 s14, s14, 0x120
	s_mul_i32 s12, s12, s14
	s_add_i32 s12, s12, s13
	s_mul_hi_i32 s13, s12, 0x38e38e39
	s_lshr_b32 s14, s13, 31
	s_ashr_i32 s13, s13, 4
	s_add_i32 s13, s13, s14
	s_lshl_b32 s14, s13, 2
	s_mulk_i32 s13, 0x48
	s_sub_i32 s12, s12, s13
	s_ashr_i32 s13, s12, 31
	s_abs_i32 s12, s12
	v_mov_b32_e32 v3, 0
	s_and_b32 s12, s12, 3
	s_add_i32 s12, s14, s12
	v_lshl_or_b32 v2, s12, 8, v153
	v_lshl_add_u64 v[2:3], v[2:3], 2, s[8:9]
	global_load_dword v109, v[2:3], off
;     __host__ __device__ bool next(int i, Unit& u) const {
;         const long L = (long)i * G + c; if (L >= nwg) return false;
;         int wgid = (int)L; { const int q = nwg / NXCD, r = nwg % NXCD, xcd = wgid % NXCD, off = wgid / NXCD; wgid = (xcd < r ? xcd * (q + 1) : r * (q + 1) + (xcd - r) * q) + off; }
;         const int nig = WGM * nN, gid = wgid / nig, fm = gid * WGM, gsz = (nM - fm) < WGM ? (nM - fm) : WGM;
;         u.pm = fm + ((wgid % nig) % gsz); u.pn = (wgid % nig) / gsz; u.idx = i; return true;
; template <class Sched>
; __device__ __forceinline__ void rstd_table(LAS float* rs, const float* ss, const Sched& S) {
;     ...
;     for (int i = 0; i < 15 && S.next(i, u); ++i) if (threadIdx.x < BM) rs[i * BM + threadIdx.x] = rsqrtf(ss[u.pm * BM + threadIdx.x] * (1.0f / DM) + NORM_EPS);
.LBB0_848:
	s_or_b64 exec, exec, s[10:11]
	s_add_u32 s6, s6, s76
	s_addc_u32 s7, s7, s0
	v_mov_b64_e32 v[2:3], 0x8ff
	v_cmp_gt_i64_e32 vcc, s[6:7], v[2:3]
	s_cbranch_vccnz .LBB0_863
	s_and_saveexec_b64 s[10:11], s[2:3]
	s_cbranch_execz .LBB0_851
	s_ashr_i32 s12, s6, 31
	s_lshr_b32 s12, s12, 29
	s_add_i32 s12, s6, s12
	s_ashr_i32 s13, s12, 3
	s_and_b32 s12, s12, -8
	s_sub_i32 s12, s6, s12
	s_cmp_lt_i32 s12, 0
	s_movk_i32 s14, 0x121
	s_cselect_b32 s14, s14, 0x120
	s_mul_i32 s12, s12, s14
	s_add_i32 s12, s12, s13
	s_mul_hi_i32 s13, s12, 0x38e38e39
	s_lshr_b32 s14, s13, 31
	s_ashr_i32 s13, s13, 4
	s_add_i32 s13, s13, s14
	s_lshl_b32 s14, s13, 2
	s_mulk_i32 s13, 0x48
	s_sub_i32 s12, s12, s13
	s_ashr_i32 s13, s12, 31
	s_abs_i32 s12, s12
	v_mov_b32_e32 v3, 0
	s_and_b32 s12, s12, 3
	s_add_i32 s12, s14, s12
	v_lshl_or_b32 v2, s12, 8, v153
	v_lshl_add_u64 v[2:3], v[2:3], 2, s[8:9]
	global_load_dword v110, v[2:3], off
.LBB0_851:
	s_or_b64 exec, exec, s[10:11]
	s_add_u32 s6, s6, s76
	s_addc_u32 s7, s7, s0
	v_mov_b64_e32 v[2:3], 0x8ff
	v_cmp_gt_i64_e32 vcc, s[6:7], v[2:3]
	s_cbranch_vccnz .LBB0_863
	s_and_saveexec_b64 s[10:11], s[2:3]
	s_cbranch_execz .LBB0_854
	s_ashr_i32 s12, s6, 31
	s_lshr_b32 s12, s12, 29
	s_add_i32 s12, s6, s12
	s_ashr_i32 s13, s12, 3
	s_and_b32 s12, s12, -8
	s_sub_i32 s12, s6, s12
	s_cmp_lt_i32 s12, 0
	s_movk_i32 s14, 0x121
	s_cselect_b32 s14, s14, 0x120
	s_mul_i32 s12, s12, s14
	s_add_i32 s12, s12, s13
	s_mul_hi_i32 s13, s12, 0x38e38e39
	s_lshr_b32 s14, s13, 31
	s_ashr_i32 s13, s13, 4
	s_add_i32 s13, s13, s14
	s_lshl_b32 s14, s13, 2
	s_mulk_i32 s13, 0x48
	s_sub_i32 s12, s12, s13
	s_ashr_i32 s13, s12, 31
	s_abs_i32 s12, s12
	v_mov_b32_e32 v3, 0
	s_and_b32 s12, s12, 3
	s_add_i32 s12, s14, s12
	v_lshl_or_b32 v2, s12, 8, v153
	v_lshl_add_u64 v[2:3], v[2:3], 2, s[8:9]
	global_load_dword v111, v[2:3], off
.LBB0_854:
	s_or_b64 exec, exec, s[10:11]
	s_add_u32 s6, s6, s76
	s_addc_u32 s7, s7, s0
	v_mov_b64_e32 v[2:3], 0x8ff
	v_cmp_gt_i64_e32 vcc, s[6:7], v[2:3]
	s_cbranch_vccnz .LBB0_863
	s_and_saveexec_b64 s[10:11], s[2:3]
	s_cbranch_execz .LBB0_857
	s_ashr_i32 s12, s6, 31
	s_lshr_b32 s12, s12, 29
	s_add_i32 s12, s6, s12
	s_ashr_i32 s13, s12, 3
	s_and_b32 s12, s12, -8
	s_sub_i32 s12, s6, s12
	s_cmp_lt_i32 s12, 0
	s_movk_i32 s14, 0x121
	s_cselect_b32 s14, s14, 0x120
	s_mul_i32 s12, s12, s14
	s_add_i32 s12, s12, s13
	s_mul_hi_i32 s13, s12, 0x38e38e39
	s_lshr_b32 s14, s13, 31
	s_ashr_i32 s13, s13, 4
	s_add_i32 s13, s13, s14
	s_lshl_b32 s14, s13, 2
	s_mulk_i32 s13, 0x48
	s_sub_i32 s12, s12, s13
	s_ashr_i32 s13, s12, 31
	s_abs_i32 s12, s12
	v_mov_b32_e32 v3, 0
	s_and_b32 s12, s12, 3
	s_add_i32 s12, s14, s12
	v_lshl_or_b32 v2, s12, 8, v153
	v_lshl_add_u64 v[2:3], v[2:3], 2, s[8:9]
	global_load_dword v112, v[2:3], off
.LBB0_857:
	s_or_b64 exec, exec, s[10:11]
	s_add_u32 s6, s6, s76
	s_addc_u32 s7, s7, s0
	v_mov_b64_e32 v[2:3], 0x8ff
	v_cmp_gt_i64_e32 vcc, s[6:7], v[2:3]
	s_cbranch_vccnz .LBB0_863
	s_and_saveexec_b64 s[10:11], s[2:3]
	s_cbranch_execz .LBB0_860
	s_ashr_i32 s12, s6, 31
	s_lshr_b32 s12, s12, 29
	s_add_i32 s12, s6, s12
	s_ashr_i32 s13, s12, 3
	s_and_b32 s12, s12, -8
	s_sub_i32 s12, s6, s12
	s_cmp_lt_i32 s12, 0
	s_movk_i32 s14, 0x121
	s_cselect_b32 s14, s14, 0x120
	s_mul_i32 s12, s12, s14
	s_add_i32 s12, s12, s13
	s_mul_hi_i32 s13, s12, 0x38e38e39
	s_lshr_b32 s14, s13, 31
	s_ashr_i32 s13, s13, 4
	s_add_i32 s13, s13, s14
	s_lshl_b32 s14, s13, 2
	s_mulk_i32 s13, 0x48
	s_sub_i32 s12, s12, s13
	s_ashr_i32 s13, s12, 31
	s_abs_i32 s12, s12
	v_mov_b32_e32 v3, 0
	s_and_b32 s12, s12, 3
	s_add_i32 s12, s14, s12
	v_lshl_or_b32 v2, s12, 8, v153
	v_lshl_add_u64 v[2:3], v[2:3], 2, s[8:9]
	global_load_dword v113, v[2:3], off
.LBB0_860:
	s_or_b64 exec, exec, s[10:11]
	s_add_u32 s6, s6, s76
	s_addc_u32 s7, s7, s0
	v_mov_b64_e32 v[2:3], 0x900
	v_cmp_lt_i64_e32 vcc, s[6:7], v[2:3]
	s_and_b64 s[10:11], vcc, s[2:3]
	s_and_saveexec_b64 s[2:3], s[10:11]
	s_cbranch_execz .LBB0_862
	s_ashr_i32 s7, s6, 31
	s_lshr_b32 s7, s7, 29
	s_add_i32 s7, s6, s7
	s_ashr_i32 s10, s7, 3
	s_and_b32 s7, s7, -8
	s_sub_i32 s6, s6, s7
	s_cmp_lt_i32 s6, 0
	s_movk_i32 s7, 0x121
	s_cselect_b32 s7, s7, 0x120
	s_mul_i32 s6, s6, s7
	s_add_i32 s6, s6, s10
	s_mul_hi_i32 s7, s6, 0x38e38e39
	s_lshr_b32 s10, s7, 31
	s_ashr_i32 s7, s7, 4
	s_add_i32 s7, s7, s10
	s_lshl_b32 s10, s7, 2
	s_mulk_i32 s7, 0x48
	s_sub_i32 s6, s6, s7
	s_ashr_i32 s7, s6, 31
	s_abs_i32 s6, s6
	v_mov_b32_e32 v3, 0
	s_and_b32 s6, s6, 3
	s_add_i32 s6, s10, s6
	v_lshl_or_b32 v2, s6, 8, v153
	v_lshl_add_u64 v[2:3], v[2:3], 2, s[8:9]
	global_load_dword v114, v[2:3], off

;     __host__ __device__ bool next(int i, Unit& u) const {
;         const long L = (long)i * G + c; if (L >= nwg) return false;
;         int wgid = (int)L; { const int q = nwg / NXCD, r = nwg % NXCD, xcd = wgid % NXCD, off = wgid / NXCD; wgid = (xcd < r ? xcd * (q + 1) : r * (q + 1) + (xcd - r) * q) + off; }
;         const int nig = WGM * nN, gid = wgid / nig, fm = gid * WGM, gsz = (nM - fm) < WGM ? (nM - fm) : WGM;
;         u.pm = fm + ((wgid % nig) % gsz); u.pn = (wgid % nig) / gsz; u.idx = i; return true;
; template <class Epi, class Sched, bool ALIGN_EPI>
; __device__ __forceinline__ void gemm_phase(LAS unsigned char* lds, const Gemm g, const Sched& S, const Epi& E) {
;     ...
;         const bool has_next = S.next(ui + 1, nxt);
.LBB0_871:
	s_add_i32 s48, s48, 1
	s_mul_i32 s4, s48, s0
	s_mul_hi_u32 s5, s48, s76
	s_add_i32 s5, s5, s4
	s_mul_i32 s4, s48, s76
	s_add_u32 s22, s4, s97
	s_addc_u32 s23, s5, s1
	v_cmp_gt_i64_e32 vcc, s[22:23], v[144:145]
	v_cmp_lt_i64_e64 s[4:5], s[22:23], v[142:143]
	s_cbranch_vccnz .LBB0_873
	s_ashr_i32 s18, s22, 31
	s_lshr_b32 s18, s18, 29
	s_add_i32 s18, s22, s18
	s_ashr_i32 s19, s18, 3
	s_and_b32 s18, s18, -8
	s_sub_i32 s18, s22, s18
	s_cmp_lt_i32 s18, 0
	s_cselect_b32 s20, s43, 0x120
	s_mul_i32 s18, s18, s20
	s_add_i32 s18, s18, s19
	s_mul_hi_i32 s19, s18, 0x38e38e39
	s_lshr_b32 s20, s19, 31
	s_ashr_i32 s19, s19, 4
	s_add_i32 s19, s19, s20
	s_lshl_b32 s20, s19, 2
	s_mulk_i32 s19, 0x48
	s_sub_i32 s19, s18, s19
	s_abs_i32 s18, s19
	s_mov_b32 s49, s48
	s_lshr_b32 s18, s19, 2
	s_and_b32 s19, s19, 3
	s_add_i32 s20, s20, s19

;     __host__ __device__ bool next(int i, Unit& u) const {
;         const long L = (long)i * G + c; if (L >= nwg) return false;
;         int wgid = (int)L; { const int q = nwg / NXCD, r = nwg % NXCD, xcd = wgid % NXCD, off = wgid / NXCD; wgid = (xcd < r ? xcd * (q + 1) : r * (q + 1) + (xcd - r) * q) + off; }
;         const int nig = WGM * nN, gid = wgid / nig, fm = gid * WGM, gsz = (nM - fm) < WGM ? (nM - fm) : WGM;
;         u.pm = fm + ((wgid % nig) % gsz); u.pn = (wgid % nig) / gsz; u.idx = i; return true;
.LBB0_1348:
	s_ashr_i32 s20, s22, 3
	s_add_i32 s20, s29, s20
	s_ashr_i32 s21, s20, 31
	s_lshr_b32 s21, s21, 28
	s_add_i32 s21, s20, s21
	s_ashr_i32 s22, s21, 4
	s_lshl_b32 s22, s22, 2
	s_and_b32 s21, s21, -16
	s_sub_i32 s21, s20, s21
	s_abs_i32 s20, s21
	s_lshr_b32 s20, s21, 2
	s_and_b32 s21, s21, 3
	s_add_i32 s22, s22, s21

;     __host__ __device__ bool next(int i, Unit& u) const {
;         const long L = (long)i * G + c; if (L >= nwg) return false;
;         int wgid = (int)L; { const int q = nwg / NXCD, r = nwg % NXCD, xcd = wgid % NXCD, off = wgid / NXCD; wgid = (xcd < r ? xcd * (q + 1) : r * (q + 1) + (xcd - r) * q) + off; }
;         const int nig = WGM * nN, gid = wgid / nig, fm = gid * WGM, gsz = (nM - fm) < WGM ? (nM - fm) : WGM;
;         u.pm = fm + ((wgid % nig) % gsz); u.pn = (wgid % nig) / gsz; u.idx = i; return true;
.LBB0_1455:
	s_ashr_i32 s18, s20, 3
	s_add_i32 s18, s22, s18
	s_ashr_i32 s19, s18, 31
	s_lshr_b32 s19, s19, 28
	s_add_i32 s19, s18, s19
	s_ashr_i32 s20, s19, 4
	s_lshl_b32 s20, s20, 2
	s_and_b32 s19, s19, -16
	s_sub_i32 s19, s18, s19
	s_abs_i32 s18, s19
	s_lshr_b32 s18, s19, 2
	s_and_b32 s19, s19, 3
	s_add_i32 s20, s20, s19

; #define LAS __attribute__((address_space(3)))
;     __host__ __device__ bool next(int i, Unit& u) const {
;         const long L = (long)i * G + c; if (L >= nwg) return false;
;         int wgid = (int)L; { const int q = nwg / NXCD, r = nwg % NXCD, xcd = wgid % NXCD, off = wgid / NXCD; wgid = (xcd < r ? xcd * (q + 1) : r * (q + 1) + (xcd - r) * q) + off; }
;         const int nig = WGM * nN, gid = wgid / nig, fm = gid * WGM, gsz = (nM - fm) < WGM ? (nM - fm) : WGM;
;         u.pm = fm + ((wgid % nig) % gsz); u.pn = (wgid % nig) / gsz; u.idx = i; return true;
; template <class Sched>
; __device__ __forceinline__ void rstd_table(LAS float* rs, const float* ss, const Sched& S) {
;     Unit u;
;     for (int i = 0; i < 15 && S.next(i, u); ++i) if (threadIdx.x < BM) rs[i * BM + threadIdx.x] = rsqrtf(ss[u.pm * BM + threadIdx.x] * (1.0f / DM) + NORM_EPS);
; }
.LBB0_1558:
	s_cmp_lt_i32 s88, 8
	s_cselect_b64 s[0:1], -1, 0
	s_cmp_gt_i32 s89, 7
	s_cselect_b64 s[2:3], -1, 0
	s_and_b64 s[0:1], s[0:1], s[2:3]
	s_andn2_b64 vcc, exec, s[0:1]
	s_waitcnt lgkmcnt(0)
	s_cbranch_vccnz .LBB0_1620
	s_ashr_i32 s0, s76, 31
	s_ashr_i32 s1, s97, 31
	s_cmpk_lt_i32 s97, 0xb00
	s_cselect_b64 s[4:5], -1, 0
	s_cmpk_gt_i32 s97, 0xaff
	s_cbranch_scc1 .LBB0_1604
	s_movk_i32 s2, 0x100
	s_add_i32 s8, 0, 0x20000
	v_cmp_gt_u32_e64 s[2:3], s2, v153
	v_lshl_add_u32 v0, v153, 2, s8
	s_and_saveexec_b64 s[8:9], s[2:3]
	s_cbranch_execz .LBB0_1562
	s_lshr_b32 s10, s1, 29
	s_add_i32 s10, s97, s10
	s_and_b32 s11, s10, -8
	s_sub_i32 s11, s97, s11
	s_cmp_lt_i32 s11, 0
	s_movk_i32 s12, 0x161
	s_cselect_b32 s12, s12, 0x160
	s_mul_i32 s11, s11, s12
	s_ashr_i32 s10, s10, 3
	s_add_i32 s11, s11, s10
	s_mul_hi_i32 s10, s11, 0x2e8ba2e9
	s_lshr_b32 s12, s10, 31
	s_ashr_i32 s10, s10, 4
	s_add_i32 s10, s10, s12
	s_lshl_b32 s12, s10, 2
	s_mulk_i32 s10, 0x58
	s_sub_i32 s10, s11, s10
	s_ashr_i32 s11, s10, 31
	s_abs_i32 s10, s10
	v_mov_b32_e32 v3, 0
	s_and_b32 s10, s10, 3
	s_add_i32 s10, s12, s10
	v_lshl_or_b32 v2, s10, 8, v153
	v_lshl_add_u64 v[2:3], v[2:3], 2, s[6:7]
	global_load_dword v100, v[2:3], off
.LBB0_1562:
	s_or_b64 exec, exec, s[8:9]
	s_add_u32 s8, s76, s97
	s_addc_u32 s9, s0, s1
	v_mov_b64_e32 v[2:3], 0xaff
	v_cmp_gt_i64_e32 vcc, s[8:9], v[2:3]
	s_cbranch_vccnz .LBB0_1604
	s_and_saveexec_b64 s[10:11], s[2:3]
	s_cbranch_execz .LBB0_1565
	s_ashr_i32 s12, s8, 31
	s_lshr_b32 s12, s12, 29
	s_add_i32 s12, s8, s12
	s_ashr_i32 s13, s12, 3
	s_and_b32 s12, s12, -8
	s_sub_i32 s12, s8, s12
	s_cmp_lt_i32 s12, 0
	s_movk_i32 s14, 0x161
	s_cselect_b32 s14, s14, 0x160
	s_mul_i32 s12, s12, s14
	s_add_i32 s12, s12, s13
	s_mul_hi_i32 s13, s12, 0x2e8ba2e9
	s_lshr_b32 s14, s13, 31
	s_ashr_i32 s13, s13, 4
	s_add_i32 s13, s13, s14
	s_lshl_b32 s14, s13, 2
	s_mulk_i32 s13, 0x58
	s_sub_i32 s12, s12, s13
	s_ashr_i32 s13, s12, 31
	s_abs_i32 s12, s12
	v_mov_b32_e32 v3, 0
	s_and_b32 s12, s12, 3
	s_add_i32 s12, s14, s12
	v_lshl_or_b32 v2, s12, 8, v153
	v_lshl_add_u64 v[2:3], v[2:3], 2, s[6:7]
	global_load_dword v101, v[2:3], off
.LBB0_1565:
	s_or_b64 exec, exec, s[10:11]
	s_add_u32 s8, s8, s76
	s_addc_u32 s9, s9, s0
	v_mov_b64_e32 v[2:3], 0xaff
	v_cmp_gt_i64_e32 vcc, s[8:9], v[2:3]
	s_cbranch_vccnz .LBB0_1604
	s_and_saveexec_b64 s[10:11], s[2:3]
	s_cbranch_execz .LBB0_1568
	s_ashr_i32 s12, s8, 31
	s_lshr_b32 s12, s12, 29
	s_add_i32 s12, s8, s12
	s_ashr_i32 s13, s12, 3
	s_and_b32 s12, s12, -8
	s_sub_i32 s12, s8, s12
	s_cmp_lt_i32 s12, 0
	s_movk_i32 s14, 0x161
	s_cselect_b32 s14, s14, 0x160
	s_mul_i32 s12, s12, s14
	s_add_i32 s12, s12, s13
	s_mul_hi_i32 s13, s12, 0x2e8ba2e9
	s_lshr_b32 s14, s13, 31
	s_ashr_i32 s13, s13, 4
	s_add_i32 s13, s13, s14
	s_lshl_b32 s14, s13, 2
	s_mulk_i32 s13, 0x58
	s_sub_i32 s12, s12, s13
	s_ashr_i32 s13, s12, 31
	s_abs_i32 s12, s12
	v_mov_b32_e32 v3, 0
	s_and_b32 s12, s12, 3
	s_add_i32 s12, s14, s12
	v_lshl_or_b32 v2, s12, 8, v153
	v_lshl_add_u64 v[2:3], v[2:3], 2, s[6:7]
	global_load_dword v102, v[2:3], off
.LBB0_1568:
	s_or_b64 exec, exec, s[10:11]
	s_add_u32 s8, s8, s76
	s_addc_u32 s9, s9, s0
	v_mov_b64_e32 v[2:3], 0xaff
	v_cmp_gt_i64_e32 vcc, s[8:9], v[2:3]
	s_cbranch_vccnz .LBB0_1604
	s_and_saveexec_b64 s[10:11], s[2:3]
	s_cbranch_execz .LBB0_1571
	s_ashr_i32 s12, s8, 31
	s_lshr_b32 s12, s12, 29
	s_add_i32 s12, s8, s12
	s_ashr_i32 s13, s12, 3
	s_and_b32 s12, s12, -8
	s_sub_i32 s12, s8, s12
	s_cmp_lt_i32 s12, 0
	s_movk_i32 s14, 0x161
	s_cselect_b32 s14, s14, 0x160
	s_mul_i32 s12, s12, s14
	s_add_i32 s12, s12, s13
	s_mul_hi_i32 s13, s12, 0x2e8ba2e9
	s_lshr_b32 s14, s13, 31
	s_ashr_i32 s13, s13, 4
	s_add_i32 s13, s13, s14
	s_lshl_b32 s14, s13, 2
	s_mulk_i32 s13, 0x58
	s_sub_i32 s12, s12, s13
	s_ashr_i32 s13, s12, 31
	s_abs_i32 s12, s12
	v_mov_b32_e32 v3, 0
	s_and_b32 s12, s12, 3
	s_add_i32 s12, s14, s12
	v_lshl_or_b32 v2, s12, 8, v153
	v_lshl_add_u64 v[2:3], v[2:3], 2, s[6:7]
	global_load_dword v103, v[2:3], off
.LBB0_1571:
	s_or_b64 exec, exec, s[10:11]
	s_add_u32 s8, s8, s76
	s_addc_u32 s9, s9, s0
	v_mov_b64_e32 v[2:3], 0xaff
	v_cmp_gt_i64_e32 vcc, s[8:9], v[2:3]
	s_cbranch_vccnz .LBB0_1604
	s_and_saveexec_b64 s[10:11], s[2:3]
	s_cbranch_execz .LBB0_1574
	s_ashr_i32 s12, s8, 31
	s_lshr_b32 s12, s12, 29
	s_add_i32 s12, s8, s12
	s_ashr_i32 s13, s12, 3
	s_and_b32 s12, s12, -8
	s_sub_i32 s12, s8, s12
	s_cmp_lt_i32 s12, 0
	s_movk_i32 s14, 0x161
	s_cselect_b32 s14, s14, 0x160
	s_mul_i32 s12, s12, s14
	s_add_i32 s12, s12, s13
	s_mul_hi_i32 s13, s12, 0x2e8ba2e9
	s_lshr_b32 s14, s13, 31
	s_ashr_i32 s13, s13, 4
	s_add_i32 s13, s13, s14
	s_lshl_b32 s14, s13, 2
	s_mulk_i32 s13, 0x58
	s_sub_i32 s12, s12, s13
	s_ashr_i32 s13, s12, 31
	s_abs_i32 s12, s12
	v_mov_b32_e32 v3, 0
	s_and_b32 s12, s12, 3
	s_add_i32 s12, s14, s12
	v_lshl_or_b32 v2, s12, 8, v153
	v_lshl_add_u64 v[2:3], v[2:3], 2, s[6:7]
	global_load_dword v104, v[2:3], off
.LBB0_1574:
	s_or_b64 exec, exec, s[10:11]
	s_add_u32 s8, s8, s76
	s_addc_u32 s9, s9, s0
	v_mov_b64_e32 v[2:3], 0xaff
	v_cmp_gt_i64_e32 vcc, s[8:9], v[2:3]
	s_cbranch_vccnz .LBB0_1604
	s_and_saveexec_b64 s[10:11], s[2:3]
	s_cbranch_execz .LBB0_1577
	s_ashr_i32 s12, s8, 31
	s_lshr_b32 s12, s12, 29
	s_add_i32 s12, s8, s12
	s_ashr_i32 s13, s12, 3
	s_and_b32 s12, s12, -8
	s_sub_i32 s12, s8, s12
	s_cmp_lt_i32 s12, 0
	s_movk_i32 s14, 0x161
	s_cselect_b32 s14, s14, 0x160
	s_mul_i32 s12, s12, s14
	s_add_i32 s12, s12, s13
	s_mul_hi_i32 s13, s12, 0x2e8ba2e9
	s_lshr_b32 s14, s13, 31
	s_ashr_i32 s13, s13, 4
	s_add_i32 s13, s13, s14
	s_lshl_b32 s14, s13, 2
	s_mulk_i32 s13, 0x58
	s_sub_i32 s12, s12, s13
	s_ashr_i32 s13, s12, 31
	s_abs_i32 s12, s12
	v_mov_b32_e32 v3, 0
	s_and_b32 s12, s12, 3
	s_add_i32 s12, s14, s12
	v_lshl_or_b32 v2, s12, 8, v153
	v_lshl_add_u64 v[2:3], v[2:3], 2, s[6:7]
	global_load_dword v105, v[2:3], off
;     __host__ __device__ bool next(int i, Unit& u) const {
;         const long L = (long)i * G + c; if (L >= nwg) return false;
;         int wgid = (int)L; { const int q = nwg / NXCD, r = nwg % NXCD, xcd = wgid % NXCD, off = wgid / NXCD; wgid = (xcd < r ? xcd * (q + 1) : r * (q + 1) + (xcd - r) * q) + off; }
;         const int nig = WGM * nN, gid = wgid / nig, fm = gid * WGM, gsz = (nM - fm) < WGM ? (nM - fm) : WGM;
;         u.pm = fm + ((wgid % nig) % gsz); u.pn = (wgid % nig) / gsz; u.idx = i; return true;
; template <class Sched>
; __device__ __forceinline__ void rstd_table(LAS float* rs, const float* ss, const Sched& S) {
;     ...
;     for (int i = 0; i < 15 && S.next(i, u); ++i) if (threadIdx.x < BM) rs[i * BM + threadIdx.x] = rsqrtf(ss[u.pm * BM + threadIdx.x] * (1.0f / DM) + NORM_EPS);
.LBB0_1577:
	s_or_b64 exec, exec, s[10:11]
	s_add_u32 s8, s8, s76
	s_addc_u32 s9, s9, s0
	v_mov_b64_e32 v[2:3], 0xaff
	v_cmp_gt_i64_e32 vcc, s[8:9], v[2:3]
	s_cbranch_vccnz .LBB0_1604
	s_and_saveexec_b64 s[10:11], s[2:3]
	s_cbranch_execz .LBB0_1580
	s_ashr_i32 s12, s8, 31
	s_lshr_b32 s12, s12, 29
	s_add_i32 s12, s8, s12
	s_ashr_i32 s13, s12, 3
	s_and_b32 s12, s12, -8
	s_sub_i32 s12, s8, s12
	s_cmp_lt_i32 s12, 0
	s_movk_i32 s14, 0x161
	s_cselect_b32 s14, s14, 0x160
	s_mul_i32 s12, s12, s14
	s_add_i32 s12, s12, s13
	s_mul_hi_i32 s13, s12, 0x2e8ba2e9
	s_lshr_b32 s14, s13, 31
	s_ashr_i32 s13, s13, 4
	s_add_i32 s13, s13, s14
	s_lshl_b32 s14, s13, 2
	s_mulk_i32 s13, 0x58
	s_sub_i32 s12, s12, s13
	s_ashr_i32 s13, s12, 31
	s_abs_i32 s12, s12
	v_mov_b32_e32 v3, 0
	s_and_b32 s12, s12, 3
	s_add_i32 s12, s14, s12
	v_lshl_or_b32 v2, s12, 8, v153
	v_lshl_add_u64 v[2:3], v[2:3], 2, s[6:7]
	global_load_dword v106, v[2:3], off
.LBB0_1580:
	s_or_b64 exec, exec, s[10:11]
	s_add_u32 s8, s8, s76
	s_addc_u32 s9, s9, s0
	v_mov_b64_e32 v[2:3], 0xaff
	v_cmp_gt_i64_e32 vcc, s[8:9], v[2:3]
	s_cbranch_vccnz .LBB0_1604
	s_and_saveexec_b64 s[10:11], s[2:3]
	s_cbranch_execz .LBB0_1583
	s_ashr_i32 s12, s8, 31
	s_lshr_b32 s12, s12, 29
	s_add_i32 s12, s8, s12
	s_ashr_i32 s13, s12, 3
	s_and_b32 s12, s12, -8
	s_sub_i32 s12, s8, s12
	s_cmp_lt_i32 s12, 0
	s_movk_i32 s14, 0x161
	s_cselect_b32 s14, s14, 0x160
	s_mul_i32 s12, s12, s14
	s_add_i32 s12, s12, s13
	s_mul_hi_i32 s13, s12, 0x2e8ba2e9
	s_lshr_b32 s14, s13, 31
	s_ashr_i32 s13, s13, 4
	s_add_i32 s13, s13, s14
	s_lshl_b32 s14, s13, 2
	s_mulk_i32 s13, 0x58
	s_sub_i32 s12, s12, s13
	s_ashr_i32 s13, s12, 31
	s_abs_i32 s12, s12
	v_mov_b32_e32 v3, 0
	s_and_b32 s12, s12, 3
	s_add_i32 s12, s14, s12
	v_lshl_or_b32 v2, s12, 8, v153
	v_lshl_add_u64 v[2:3], v[2:3], 2, s[6:7]
	global_load_dword v107, v[2:3], off
.LBB0_1583:
	s_or_b64 exec, exec, s[10:11]
	s_add_u32 s8, s8, s76
	s_addc_u32 s9, s9, s0
	v_mov_b64_e32 v[2:3], 0xaff
	v_cmp_gt_i64_e32 vcc, s[8:9], v[2:3]
	s_cbranch_vccnz .LBB0_1604
	s_and_saveexec_b64 s[10:11], s[2:3]
	s_cbranch_execz .LBB0_1586
	s_ashr_i32 s12, s8, 31
	s_lshr_b32 s12, s12, 29
	s_add_i32 s12, s8, s12
	s_ashr_i32 s13, s12, 3
	s_and_b32 s12, s12, -8
	s_sub_i32 s12, s8, s12
	s_cmp_lt_i32 s12, 0
	s_movk_i32 s14, 0x161
	s_cselect_b32 s14, s14, 0x160
	s_mul_i32 s12, s12, s14
	s_add_i32 s12, s12, s13
	s_mul_hi_i32 s13, s12, 0x2e8ba2e9
	s_lshr_b32 s14, s13, 31
	s_ashr_i32 s13, s13, 4
	s_add_i32 s13, s13, s14
	s_lshl_b32 s14, s13, 2
	s_mulk_i32 s13, 0x58
	s_sub_i32 s12, s12, s13
	s_ashr_i32 s13, s12, 31
	s_abs_i32 s12, s12
	v_mov_b32_e32 v3, 0
	s_and_b32 s12, s12, 3
	s_add_i32 s12, s14, s12
	v_lshl_or_b32 v2, s12, 8, v153
	v_lshl_add_u64 v[2:3], v[2:3], 2, s[6:7]
	global_load_dword v108, v[2:3], off
.LBB0_1586:
	s_or_b64 exec, exec, s[10:11]
	s_add_u32 s8, s8, s76
	s_addc_u32 s9, s9, s0
	v_mov_b64_e32 v[2:3], 0xaff
	v_cmp_gt_i64_e32 vcc, s[8:9], v[2:3]
	s_cbranch_vccnz .LBB0_1604
	s_and_saveexec_b64 s[10:11], s[2:3]
	s_cbranch_execz .LBB0_1589
	s_ashr_i32 s12, s8, 31
	s_lshr_b32 s12, s12, 29
	s_add_i32 s12, s8, s12
	s_ashr_i32 s13, s12, 3
	s_and_b32 s12, s12, -8
	s_sub_i32 s12, s8, s12
	s_cmp_lt_i32 s12, 0
	s_movk_i32 s14, 0x161
	s_cselect_b32 s14, s14, 0x160
	s_mul_i32 s12, s12, s14
	s_add_i32 s12, s12, s13
	s_mul_hi_i32 s13, s12, 0x2e8ba2e9
	s_lshr_b32 s14, s13, 31
	s_ashr_i32 s13, s13, 4
	s_add_i32 s13, s13, s14
	s_lshl_b32 s14, s13, 2
	s_mulk_i32 s13, 0x58
	s_sub_i32 s12, s12, s13
	s_ashr_i32 s13, s12, 31
	s_abs_i32 s12, s12
	v_mov_b32_e32 v3, 0
	s_and_b32 s12, s12, 3
	s_add_i32 s12, s14, s12
	v_lshl_or_b32 v2, s12, 8, v153
	v_lshl_add_u64 v[2:3], v[2:3], 2, s[6:7]
	global_load_dword v109, v[2:3], off
;     __host__ __device__ bool next(int i, Unit& u) const {
;         const long L = (long)i * G + c; if (L >= nwg) return false;
;         int wgid = (int)L; { const int q = nwg / NXCD, r = nwg % NXCD, xcd = wgid % NXCD, off = wgid / NXCD; wgid = (xcd < r ? xcd * (q + 1) : r * (q + 1) + (xcd - r) * q) + off; }
;         const int nig = WGM * nN, gid = wgid / nig, fm = gid * WGM, gsz = (nM - fm) < WGM ? (nM - fm) : WGM;
;         u.pm = fm + ((wgid % nig) % gsz); u.pn = (wgid % nig) / gsz; u.idx = i; return true;
; template <class Sched>
; __device__ __forceinline__ void rstd_table(LAS float* rs, const float* ss, const Sched& S) {
;     ...
;     for (int i = 0; i < 15 && S.next(i, u); ++i) if (threadIdx.x < BM) rs[i * BM + threadIdx.x] = rsqrtf(ss[u.pm * BM + threadIdx.x] * (1.0f / DM) + NORM_EPS);
.LBB0_1589:
	s_or_b64 exec, exec, s[10:11]
	s_add_u32 s8, s8, s76
	s_addc_u32 s9, s9, s0
	v_mov_b64_e32 v[2:3], 0xaff
	v_cmp_gt_i64_e32 vcc, s[8:9], v[2:3]
	s_cbranch_vccnz .LBB0_1604
	s_and_saveexec_b64 s[10:11], s[2:3]
	s_cbranch_execz .LBB0_1592
	s_ashr_i32 s12, s8, 31
	s_lshr_b32 s12, s12, 29
	s_add_i32 s12, s8, s12
	s_ashr_i32 s13, s12, 3
	s_and_b32 s12, s12, -8
	s_sub_i32 s12, s8, s12
	s_cmp_lt_i32 s12, 0
	s_movk_i32 s14, 0x161
	s_cselect_b32 s14, s14, 0x160
	s_mul_i32 s12, s12, s14
	s_add_i32 s12, s12, s13
	s_mul_hi_i32 s13, s12, 0x2e8ba2e9
	s_lshr_b32 s14, s13, 31
	s_ashr_i32 s13, s13, 4
	s_add_i32 s13, s13, s14
	s_lshl_b32 s14, s13, 2
	s_mulk_i32 s13, 0x58
	s_sub_i32 s12, s12, s13
	s_ashr_i32 s13, s12, 31
	s_abs_i32 s12, s12
	v_mov_b32_e32 v3, 0
	s_and_b32 s12, s12, 3
	s_add_i32 s12, s14, s12
	v_lshl_or_b32 v2, s12, 8, v153
	v_lshl_add_u64 v[2:3], v[2:3], 2, s[6:7]
	global_load_dword v110, v[2:3], off
.LBB0_1592:
	s_or_b64 exec, exec, s[10:11]
	s_add_u32 s8, s8, s76
	s_addc_u32 s9, s9, s0
	v_mov_b64_e32 v[2:3], 0xaff
	v_cmp_gt_i64_e32 vcc, s[8:9], v[2:3]
	s_cbranch_vccnz .LBB0_1604
	s_and_saveexec_b64 s[10:11], s[2:3]
	s_cbranch_execz .LBB0_1595
	s_ashr_i32 s12, s8, 31
	s_lshr_b32 s12, s12, 29
	s_add_i32 s12, s8, s12
	s_ashr_i32 s13, s12, 3
	s_and_b32 s12, s12, -8
	s_sub_i32 s12, s8, s12
	s_cmp_lt_i32 s12, 0
	s_movk_i32 s14, 0x161
	s_cselect_b32 s14, s14, 0x160
	s_mul_i32 s12, s12, s14
	s_add_i32 s12, s12, s13
	s_mul_hi_i32 s13, s12, 0x2e8ba2e9
	s_lshr_b32 s14, s13, 31
	s_ashr_i32 s13, s13, 4
	s_add_i32 s13, s13, s14
	s_lshl_b32 s14, s13, 2
	s_mulk_i32 s13, 0x58
	s_sub_i32 s12, s12, s13
	s_ashr_i32 s13, s12, 31
	s_abs_i32 s12, s12
	v_mov_b32_e32 v3, 0
	s_and_b32 s12, s12, 3
	s_add_i32 s12, s14, s12
	v_lshl_or_b32 v2, s12, 8, v153
	v_lshl_add_u64 v[2:3], v[2:3], 2, s[6:7]
	global_load_dword v111, v[2:3], off
.LBB0_1595:
	s_or_b64 exec, exec, s[10:11]
	s_add_u32 s8, s8, s76
	s_addc_u32 s9, s9, s0
	v_mov_b64_e32 v[2:3], 0xaff
	v_cmp_gt_i64_e32 vcc, s[8:9], v[2:3]
	s_cbranch_vccnz .LBB0_1604
	s_and_saveexec_b64 s[10:11], s[2:3]
	s_cbranch_execz .LBB0_1598
	s_ashr_i32 s12, s8, 31
	s_lshr_b32 s12, s12, 29
	s_add_i32 s12, s8, s12
	s_ashr_i32 s13, s12, 3
	s_and_b32 s12, s12, -8
	s_sub_i32 s12, s8, s12
	s_cmp_lt_i32 s12, 0
	s_movk_i32 s14, 0x161
	s_cselect_b32 s14, s14, 0x160
	s_mul_i32 s12, s12, s14
	s_add_i32 s12, s12, s13
	s_mul_hi_i32 s13, s12, 0x2e8ba2e9
	s_lshr_b32 s14, s13, 31
	s_ashr_i32 s13, s13, 4
	s_add_i32 s13, s13, s14
	s_lshl_b32 s14, s13, 2
	s_mulk_i32 s13, 0x58
	s_sub_i32 s12, s12, s13
	s_ashr_i32 s13, s12, 31
	s_abs_i32 s12, s12
	v_mov_b32_e32 v3, 0
	s_and_b32 s12, s12, 3
	s_add_i32 s12, s14, s12
	v_lshl_or_b32 v2, s12, 8, v153
	v_lshl_add_u64 v[2:3], v[2:3], 2, s[6:7]
	global_load_dword v112, v[2:3], off
.LBB0_1598:
	s_or_b64 exec, exec, s[10:11]
	s_add_u32 s8, s8, s76
	s_addc_u32 s9, s9, s0
	v_mov_b64_e32 v[2:3], 0xaff
	v_cmp_gt_i64_e32 vcc, s[8:9], v[2:3]
	s_cbranch_vccnz .LBB0_1604
	s_and_saveexec_b64 s[10:11], s[2:3]
	s_cbranch_execz .LBB0_1601
	s_ashr_i32 s12, s8, 31
	s_lshr_b32 s12, s12, 29
	s_add_i32 s12, s8, s12
	s_ashr_i32 s13, s12, 3
	s_and_b32 s12, s12, -8
	s_sub_i32 s12, s8, s12
	s_cmp_lt_i32 s12, 0
	s_movk_i32 s14, 0x161
	s_cselect_b32 s14, s14, 0x160
	s_mul_i32 s12, s12, s14
	s_add_i32 s12, s12, s13
	s_mul_hi_i32 s13, s12, 0x2e8ba2e9
	s_lshr_b32 s14, s13, 31
	s_ashr_i32 s13, s13, 4
	s_add_i32 s13, s13, s14
	s_lshl_b32 s14, s13, 2
	s_mulk_i32 s13, 0x58
	s_sub_i32 s12, s12, s13
	s_ashr_i32 s13, s12, 31
	s_abs_i32 s12, s12
	v_mov_b32_e32 v3, 0
	s_and_b32 s12, s12, 3
	s_add_i32 s12, s14, s12
	v_lshl_or_b32 v2, s12, 8, v153
	v_lshl_add_u64 v[2:3], v[2:3], 2, s[6:7]
	global_load_dword v113, v[2:3], off
.LBB0_1601:
	s_or_b64 exec, exec, s[10:11]
	s_add_u32 s8, s8, s76
	s_addc_u32 s9, s9, s0
	v_mov_b64_e32 v[2:3], 0xb00
	v_cmp_lt_i64_e32 vcc, s[8:9], v[2:3]
	s_and_b64 s[10:11], vcc, s[2:3]
	s_and_saveexec_b64 s[2:3], s[10:11]
	s_cbranch_execz .LBB0_1603
	s_ashr_i32 s9, s8, 31
	s_lshr_b32 s9, s9, 29
	s_add_i32 s9, s8, s9
	s_ashr_i32 s10, s9, 3
	s_and_b32 s9, s9, -8
	s_sub_i32 s8, s8, s9
	s_cmp_lt_i32 s8, 0
	s_movk_i32 s9, 0x161
	s_cselect_b32 s9, s9, 0x160
	s_mul_i32 s8, s8, s9
	s_add_i32 s8, s8, s10
	s_mul_hi_i32 s9, s8, 0x2e8ba2e9
	s_lshr_b32 s10, s9, 31
	s_ashr_i32 s9, s9, 4
	s_add_i32 s9, s9, s10
	s_lshl_b32 s10, s9, 2
	s_mulk_i32 s9, 0x58
	s_sub_i32 s8, s8, s9
	s_ashr_i32 s9, s8, 31
	s_abs_i32 s8, s8
	v_mov_b32_e32 v3, 0
	s_and_b32 s8, s8, 3
	s_add_i32 s8, s10, s8
	v_lshl_or_b32 v2, s8, 8, v153
	v_lshl_add_u64 v[2:3], v[2:3], 2, s[6:7]
	global_load_dword v114, v[2:3], off

;     __host__ __device__ bool next(int i, Unit& u) const {
;         const long L = (long)i * G + c; if (L >= nwg) return false;
;         int wgid = (int)L; { const int q = nwg / NXCD, r = nwg % NXCD, xcd = wgid % NXCD, off = wgid / NXCD; wgid = (xcd < r ? xcd * (q + 1) : r * (q + 1) + (xcd - r) * q) + off; }
;         const int nig = WGM * nN, gid = wgid / nig, fm = gid * WGM, gsz = (nM - fm) < WGM ? (nM - fm) : WGM;
;         u.pm = fm + ((wgid % nig) % gsz); u.pn = (wgid % nig) / gsz; u.idx = i; return true;
; template <class Epi, class Sched, bool ALIGN_EPI>
; __device__ __forceinline__ void gemm_phase(LAS unsigned char* lds, const Gemm g, const Sched& S, const Epi& E) {
;     ...
;         const bool has_next = S.next(ui + 1, nxt);
.LBB0_1610:
	s_add_i32 s41, s41, 1
	s_mul_i32 s2, s41, s0
	s_mul_hi_u32 s3, s41, s76
	s_add_i32 s3, s3, s2
	s_mul_i32 s2, s41, s76
	s_add_u32 s14, s2, s97
	s_addc_u32 s15, s3, s1
	v_cmp_gt_i64_e32 vcc, s[14:15], v[142:143]
	v_cmp_lt_i64_e64 s[2:3], s[14:15], v[140:141]
	s_cbranch_vccnz .LBB0_1612
	s_ashr_i32 s10, s14, 31
	s_lshr_b32 s10, s10, 29
	s_add_i32 s10, s14, s10
	s_ashr_i32 s11, s10, 3
	s_and_b32 s10, s10, -8
	s_sub_i32 s10, s14, s10
	s_cmp_lt_i32 s10, 0
	s_cselect_b32 s12, s31, 0x160
	s_mul_i32 s10, s10, s12
	s_add_i32 s10, s10, s11
	s_mul_hi_i32 s11, s10, 0x2e8ba2e9
	s_lshr_b32 s12, s11, 31
	s_ashr_i32 s11, s11, 4
	s_add_i32 s11, s11, s12
	s_lshl_b32 s12, s11, 2
	s_mulk_i32 s11, 0x58
	s_sub_i32 s11, s10, s11
	s_abs_i32 s10, s11
	s_mov_b32 s42, s41
	s_lshr_b32 s10, s11, 2
	s_and_b32 s11, s11, 3
	s_add_i32 s12, s12, s11

;     __host__ __device__ bool next(int i, Unit& u) const {
;         const long L = (long)i * G + c; if (L >= nwg) return false;
;         int wgid = (int)L; { const int q = nwg / NXCD, r = nwg % NXCD, xcd = wgid % NXCD, off = wgid / NXCD; wgid = (xcd < r ? xcd * (q + 1) : r * (q + 1) + (xcd - r) * q) + off; }
;         const int nig = WGM * nN, gid = wgid / nig, fm = gid * WGM, gsz = (nM - fm) < WGM ? (nM - fm) : WGM;
;         u.pm = fm + ((wgid % nig) % gsz); u.pn = (wgid % nig) / gsz; u.idx = i; return true;
.LBB0_1716:
	s_ashr_i32 s4, s18, 3
	s_add_i32 s4, s20, s4
	s_ashr_i32 s5, s4, 31
	s_lshr_b32 s5, s5, 28
	s_add_i32 s5, s4, s5
	s_ashr_i32 s18, s5, 4
	s_lshl_b32 s18, s18, 2
	s_and_b32 s5, s5, -16
	s_sub_i32 s4, s4, s5
	s_abs_i32 s5, s4
	s_lshr_b32 s44, s4, 2
	s_and_b32 s4, s4, 3
	s_add_i32 s45, s18, s4
